# all deferred weight-image tiles [832,5952) in the phase 3 idle slot with a hand-written software-pipelined transpose loop (wg>=128); phase 0 keeps wt_gla_in only
# speedup vs baseline: 1.0179x; 1.0179x over previous
.LBB0_21:
	s_load_dwordx16 s[68:83], s[0:1], 0x40
	v_add_u32_e32 v24, s3, v14
	v_add_u32_e32 v25, 0x1400, v24
	v_cmp_lt_i32_e32 vcc, 0x33f, v24
	s_nop 1
	v_cndmask_b32_e32 v24, v24, v25, vcc
	s_movk_i32 s4, 0x33f
	v_cmp_lt_i32_e32 vcc, s4, v24
	v_mov_b64_e32 v[6:7], 0xc10
	v_mov_b32_e32 v22, 0x400
	v_mov_b32_e32 v25, 0xc10
	v_mov_b64_e32 v[4:5], s[60:61]
	s_waitcnt lgkmcnt(0)
	v_mov_b64_e32 v[10:11], s[74:75]
	s_mov_b64 s[6:7], -1
	s_and_saveexec_b64 s[4:5], vcc
	s_cbranch_execz .LBB0_39
	s_load_dwordx16 s[68:83], s[0:1], 0x40
	s_movk_i32 s6, 0x43f
	v_cmp_lt_u32_e32 vcc, s6, v24
	v_mov_b64_e32 v[4:5], s[62:63]
	s_waitcnt lgkmcnt(0)
	v_mov_b64_e32 v[10:11], s[82:83]
	s_and_saveexec_b64 s[8:9], vcc
	s_xor_b64 s[8:9], exec, s[8:9]
	s_cbranch_execz .LBB0_36
	s_movk_i32 s6, 0xc3f
	v_cmp_lt_u32_e32 vcc, s6, v24
	s_and_saveexec_b64 s[10:11], vcc
	s_xor_b64 s[10:11], exec, s[10:11]
	s_cbranch_execz .LBB0_33
	s_movk_i32 s6, 0x143f
	v_cmp_lt_u32_e32 vcc, s6, v24
	s_and_saveexec_b64 s[12:13], vcc
	s_xor_b64 s[12:13], exec, s[12:13]
	s_cbranch_execz .LBB0_30
	s_load_dwordx16 s[68:83], s[0:1], 0x80
	s_movk_i32 s6, 0x153f
	v_cmp_lt_u32_e32 vcc, s6, v24
	v_mov_b64_e32 v[4:5], s[36:37]
	s_waitcnt lgkmcnt(0)
	v_mov_b64_e32 v[10:11], s[68:69]
	s_and_saveexec_b64 s[6:7], vcc
	s_xor_b64 s[6:7], exec, s[6:7]
	v_add_u32_e32 v24, 0xffffeac0, v24
	v_mov_b64_e32 v[10:11], s[54:55]
	v_mov_b64_e32 v[4:5], s[38:39]
	s_or_saveexec_b64 s[14:15], s[6:7]
	s_mov_b64 s[6:7], 0
	v_mov_b32_e32 v25, 0x800
	s_xor_b64 exec, exec, s[14:15]
	s_mov_b64 s[6:7], exec
	v_add_u32_e32 v24, 0xffffebc0, v24
	v_mov_b32_e32 v25, 0x400
	s_or_b64 exec, exec, s[14:15]

.LBB0_165:
	s_cmp_lt_u32 s2, 64
	s_cbranch_scc1 .Ltr1_skip
	s_sub_u32 s3, s2, 64
	s_lshl_b32 s3, s3, 1
	s_addk_i32 s3, 0x340
	s_cmpk_gt_i32 s3, 0x33f
	s_cbranch_scc1 .Ltr1_75
	s_load_dwordx4 s[84:87], s[0:1], 0x100
	s_load_dwordx4 s[88:91], s[0:1], 0xc8
	s_waitcnt lgkmcnt(0)
	s_barrier
	v_lshlrev_b32_e32 v0, 3, v129
	v_lshrrev_b32_e32 v14, 8, v129
	v_and_b32_e32 v0, 56, v0
	v_bfe_u32 v18, v129, 3, 5
	v_lshl_add_u32 v2, v14, 15, 0
	v_and_b32_e32 v15, 63, v129
	v_and_b32_e32 v3, 16, v129
	v_mul_u32_u24_e32 v5, 0x104, v0
	v_lshlrev_b32_e32 v6, 2, v18
	v_bfe_u32 v16, v129, 6, 2
	v_lshl_add_u32 v4, v15, 2, v2
	v_add3_u32 v19, v2, v5, v6
	v_mov_b32_e32 v2, s91
	v_mov_b32_e32 v6, s89
	v_cmp_eq_u32_e32 vcc, 0, v3
	v_mul_u32_u24_e32 v5, 0x104, v16
	v_and_b32_e32 v17, 15, v129
	v_cndmask_b32_e32 v3, v2, v6, vcc
	v_mov_b32_e32 v2, s90
	v_mov_b32_e32 v6, s88
	v_mov_b32_e32 v1, 0
	s_waitcnt lgkmcnt(0)
	s_movk_i32 s16, 0x180
	v_or_b32_e32 v20, 32, v18
	v_cndmask_b32_e32 v2, v2, v6, vcc
	v_add_u32_e32 v21, v4, v5
	v_lshlrev_b32_e32 v0, 1, v0
	s_branch .Ltr1_21

.LBB0_362:
	s_cmp_lt_u32 s2, 128
	s_cbranch_scc1 .Ltrq_skip
	s_sub_u32 s3, s2, 128
	s_lshl_b32 s3, s3, 1
	s_addk_i32 s3, 0x340
	s_cmpk_gt_i32 s3, 0x173f
	s_cbranch_scc1 .Ltrq_done
	s_load_dwordx4 s[72:75], s[0:1], 0x48
	s_load_dwordx2 s[76:77], s[0:1], 0x78
	s_load_dwordx2 s[78:79], s[0:1], 0x80
	s_load_dwordx4 s[80:83], s[0:1], 0xc8
	s_load_dwordx4 s[84:87], s[0:1], 0x100
	v_and_b32_e32 v32, 63, v129
	v_lshlrev_b32_e32 v82, 2, v32
	v_mov_b32_e32 v83, 0
	v_lshrrev_b32_e32 v84, 5, v32
	v_lshlrev_b32_e32 v84, 4, v84
	v_and_b32_e32 v85, 15, v32
	v_add_u32_e32 v84, v84, v85
	v_lshlrev_b32_e32 v84, 2, v84
	v_mov_b32_e32 v85, 0
	v_and_b32_e32 v37, 16, v32
	v_cmp_ne_u32_e64 s[68:69], 0, v37
	v_readfirstlane_b32 s4, v129
	s_lshr_b32 s4, s4, 6
	s_lshr_b32 s5, s4, 2
	s_and_b32 s6, s4, 3
	s_lshl_b32 s7, s5, 15
	s_mul_i32 s8, s6, 0x104
	s_add_u32 s8, s7, s8
	v_add_u32_e32 v38, s8, v82
	v_and_b32_e32 v39, 7, v129
	v_lshlrev_b32_e32 v39, 3, v39
	v_mul_u32_u24_e32 v40, 0x104, v39
	v_bfe_u32 v41, v129, 3, 5
	v_lshl_add_u32 v40, v41, 2, v40
	v_add_u32_e32 v40, s7, v40
	v_add_u32_e32 v44, 0x400, v40
	v_lshlrev_b32_e32 v42, 1, v39
	v_mov_b32_e32 v47, 0
	s_add_u32 s9, s3, s5
	s_waitcnt lgkmcnt(0)
	s_cmpk_lt_u32 s9, 0x440
	s_cbranch_scc1 .Ltrq_p1_c0
	s_cmpk_lt_u32 s9, 0xc40
	s_cbranch_scc1 .Ltrq_p1_c1
	s_cmpk_lt_u32 s9, 0x1440
	s_cbranch_scc1 .Ltrq_p1_c2
	s_cmpk_lt_u32 s9, 0x1540
	s_cbranch_scc1 .Ltrq_p1_c3
	s_sub_u32 s7, s9, 0x1540
	s_mov_b64 s[70:71], s[80:81]
	s_mov_b64 s[12:13], s[82:83]
	s_mov_b64 s[16:17], s[86:87]
	s_mov_b32 s8, 10
	s_mov_b32 s22, 10
	s_mov_b32 s21, 1
	s_branch .Ltrq_p1_cm
.Ltrq_p1_c0:
	s_sub_u32 s7, s9, 0x340
	s_mov_b64 s[70:71], s[76:77]
	s_mov_b64 s[16:17], s[62:63]
	s_mov_b32 s8, 10
	s_mov_b32 s22, 10
	s_mov_b32 s21, 0
	s_branch .Ltrq_p1_cm
.Ltrq_p1_c1:
	s_sub_u32 s7, s9, 0x440
	s_lshr_b32 s23, s7, 10
	s_and_b32 s7, s7, 0x3ff
	s_lshl_b32 s32, s23, 24
	s_add_u32 s70, s72, s32
	s_addc_u32 s71, s73, 0
	s_lshl_b32 s32, s23, 23
	s_add_u32 s16, s64, s32
	s_addc_u32 s17, s65, 0
	s_mov_b32 s8, 12
	s_mov_b32 s22, 10
	s_mov_b32 s21, 0
	s_branch .Ltrq_p1_cm
.Ltrq_p1_c2:
	s_sub_u32 s7, s9, 0xc40
	s_lshr_b32 s23, s7, 10
	s_and_b32 s7, s7, 0x3ff
	s_lshl_b32 s32, s23, 24
	s_add_u32 s70, s74, s32
	s_addc_u32 s71, s75, 0
	s_lshl_b32 s32, s23, 23
	s_add_u32 s16, s66, s32
	s_addc_u32 s17, s67, 0
	s_mov_b32 s8, 10
	s_mov_b32 s22, 12
	s_mov_b32 s21, 0
	s_branch .Ltrq_p1_cm
.Ltrq_p1_c3:
	s_sub_u32 s7, s9, 0x1440
	s_mov_b64 s[70:71], s[78:79]
	s_mov_b64 s[16:17], s[84:85]
	s_mov_b32 s8, 10
	s_mov_b32 s22, 10
	s_mov_b32 s21, 0
.Ltrq_p1_cm:
	s_sub_u32 s23, s22, 6
	s_lshr_b32 s32, s7, s23
	s_lshl_b32 s32, s32, 6
	s_bfm_b32 s23, s23, 0
	s_and_b32 s7, s7, s23
	s_lshl_b32 s7, s7, 6
	s_lshl_b32 s23, s32, s22
	s_add_u32 s23, s23, s7
	s_lshl_b32 s23, s23, 1
	s_add_u32 s16, s16, s23
	s_addc_u32 s17, s17, 0
	s_add_u32 s7, s7, s6
	s_add_u32 s23, s8, 2
	s_mov_b32 s15, 0
	s_mov_b32 s14, s7
	s_lshl_b64 s[14:15], s[14:15], s23
	s_sub_u32 s23, 2, s21
	s_lshl_b32 s32, s32, s23
	s_add_u32 s14, s14, s32
	s_addc_u32 s15, s15, 0
	s_add_u32 s12, s12, s14
	s_addc_u32 s13, s13, s15
	s_add_u32 s10, s70, s14
	s_addc_u32 s11, s71, s15
	s_add_u32 s23, s8, 4
	s_lshl_b32 s14, 1, s23
	s_mov_b32 s15, 0
	s_add_u32 s23, s22, 6
	s_lshl_b32 s18, 1, s23
	s_mov_b32 s19, 0
	s_add_u32 s20, s22, 1
	s_cmp_eq_u32 s21, 0
	s_cbranch_scc0 .Ltrq_l2_g
	v_lshl_add_u64 v[60:61], s[10:11], 0, v[82:83]
	s_branch .Ltrq_l2_x
.Ltrq_l2_g:
	v_lshl_add_u64 v[60:61], s[10:11], 0, v[84:85]
	v_lshl_add_u64 v[64:65], s[12:13], 0, v[84:85]
	s_nop 0
	v_cndmask_b32_e64 v60, v60, v64, s[68:69]
	v_cndmask_b32_e64 v61, v61, v65, s[68:69]
.Ltrq_l2_x:
	global_load_dword v0, v[60:61], off
	v_lshl_add_u64 v[60:61], v[60:61], 0, s[14:15]
	global_load_dword v1, v[60:61], off
	v_lshl_add_u64 v[60:61], v[60:61], 0, s[14:15]
	global_load_dword v2, v[60:61], off
	v_lshl_add_u64 v[60:61], v[60:61], 0, s[14:15]
	global_load_dword v3, v[60:61], off
	v_lshl_add_u64 v[60:61], v[60:61], 0, s[14:15]
	global_load_dword v4, v[60:61], off
	v_lshl_add_u64 v[60:61], v[60:61], 0, s[14:15]
	global_load_dword v5, v[60:61], off
	v_lshl_add_u64 v[60:61], v[60:61], 0, s[14:15]
	global_load_dword v6, v[60:61], off
	v_lshl_add_u64 v[60:61], v[60:61], 0, s[14:15]
	global_load_dword v7, v[60:61], off
	v_lshl_add_u64 v[60:61], v[60:61], 0, s[14:15]
	global_load_dword v8, v[60:61], off
	v_lshl_add_u64 v[60:61], v[60:61], 0, s[14:15]
	global_load_dword v9, v[60:61], off
	v_lshl_add_u64 v[60:61], v[60:61], 0, s[14:15]
	global_load_dword v10, v[60:61], off
	v_lshl_add_u64 v[60:61], v[60:61], 0, s[14:15]
	global_load_dword v11, v[60:61], off
	v_lshl_add_u64 v[60:61], v[60:61], 0, s[14:15]
	global_load_dword v12, v[60:61], off
	v_lshl_add_u64 v[60:61], v[60:61], 0, s[14:15]
	global_load_dword v13, v[60:61], off
	v_lshl_add_u64 v[60:61], v[60:61], 0, s[14:15]
	global_load_dword v14, v[60:61], off
	v_lshl_add_u64 v[60:61], v[60:61], 0, s[14:15]
	global_load_dword v15, v[60:61], off
.Ltrq_loop:
	s_addk_i32 s9, 0x100
	s_cmpk_lt_u32 s9, 0x1740
	s_cbranch_scc0 .Ltrq_last1
	s_cmpk_lt_u32 s9, 0x440
	s_cbranch_scc1 .Ltrq_p3_c0
	s_cmpk_lt_u32 s9, 0xc40
	s_cbranch_scc1 .Ltrq_p3_c1
	s_cmpk_lt_u32 s9, 0x1440
	s_cbranch_scc1 .Ltrq_p3_c2
	s_cmpk_lt_u32 s9, 0x1540
	s_cbranch_scc1 .Ltrq_p3_c3
	s_sub_u32 s7, s9, 0x1540
	s_mov_b64 s[70:71], s[80:81]
	s_mov_b64 s[28:29], s[82:83]
	s_mov_b64 s[34:35], s[86:87]
	s_mov_b32 s8, 10
	s_mov_b32 s22, 10
	s_mov_b32 s91, 1
	s_branch .Ltrq_p3_cm
.Ltrq_p3_c0:
	s_sub_u32 s7, s9, 0x340
	s_mov_b64 s[70:71], s[76:77]
	s_mov_b64 s[34:35], s[62:63]
	s_mov_b32 s8, 10
	s_mov_b32 s22, 10
	s_mov_b32 s91, 0
	s_branch .Ltrq_p3_cm
.Ltrq_p3_c1:
	s_sub_u32 s7, s9, 0x440
	s_lshr_b32 s23, s7, 10
	s_and_b32 s7, s7, 0x3ff
	s_lshl_b32 s32, s23, 24
	s_add_u32 s70, s72, s32
	s_addc_u32 s71, s73, 0
	s_lshl_b32 s32, s23, 23
	s_add_u32 s34, s64, s32
	s_addc_u32 s35, s65, 0
	s_mov_b32 s8, 12
	s_mov_b32 s22, 10
	s_mov_b32 s91, 0
	s_branch .Ltrq_p3_cm
.Ltrq_p3_c2:
	s_sub_u32 s7, s9, 0xc40
	s_lshr_b32 s23, s7, 10
	s_and_b32 s7, s7, 0x3ff
	s_lshl_b32 s32, s23, 24
	s_add_u32 s70, s74, s32
	s_addc_u32 s71, s75, 0
	s_lshl_b32 s32, s23, 23
	s_add_u32 s34, s66, s32
	s_addc_u32 s35, s67, 0
	s_mov_b32 s8, 10
	s_mov_b32 s22, 12
	s_mov_b32 s91, 0
	s_branch .Ltrq_p3_cm
.Ltrq_p3_c3:
	s_sub_u32 s7, s9, 0x1440
	s_mov_b64 s[70:71], s[78:79]
	s_mov_b64 s[34:35], s[84:85]
	s_mov_b32 s8, 10
	s_mov_b32 s22, 10
	s_mov_b32 s91, 0
.Ltrq_p3_cm:
	s_sub_u32 s23, s22, 6
	s_lshr_b32 s32, s7, s23
	s_lshl_b32 s32, s32, 6
	s_bfm_b32 s23, s23, 0
	s_and_b32 s7, s7, s23
	s_lshl_b32 s7, s7, 6
	s_lshl_b32 s23, s32, s22
	s_add_u32 s23, s23, s7
	s_lshl_b32 s23, s23, 1
	s_add_u32 s34, s34, s23
	s_addc_u32 s35, s35, 0
	s_add_u32 s7, s7, s6
	s_add_u32 s23, s8, 2
	s_mov_b32 s31, 0
	s_mov_b32 s30, s7
	s_lshl_b64 s[30:31], s[30:31], s23
	s_sub_u32 s23, 2, s91
	s_lshl_b32 s32, s32, s23
	s_add_u32 s30, s30, s32
	s_addc_u32 s31, s31, 0
	s_add_u32 s28, s28, s30
	s_addc_u32 s29, s29, s31
	s_add_u32 s26, s70, s30
	s_addc_u32 s27, s71, s31
	s_add_u32 s23, s8, 4
	s_lshl_b32 s30, 1, s23
	s_mov_b32 s31, 0
	s_add_u32 s23, s22, 6
	s_lshl_b32 s88, 1, s23
	s_mov_b32 s89, 0
	s_add_u32 s90, s22, 1
	s_cmp_eq_u32 s91, 0
	s_cbranch_scc0 .Ltrq_l4_g
	v_lshl_add_u64 v[62:63], s[26:27], 0, v[82:83]
	s_branch .Ltrq_l4_x
.Ltrq_l4_g:
	v_lshl_add_u64 v[62:63], s[26:27], 0, v[84:85]
	v_lshl_add_u64 v[64:65], s[28:29], 0, v[84:85]
	s_nop 0
	v_cndmask_b32_e64 v62, v62, v64, s[68:69]
	v_cndmask_b32_e64 v63, v63, v65, s[68:69]
.Ltrq_l4_x:
	global_load_dword v16, v[62:63], off
	v_lshl_add_u64 v[62:63], v[62:63], 0, s[30:31]
	global_load_dword v17, v[62:63], off
	v_lshl_add_u64 v[62:63], v[62:63], 0, s[30:31]
	global_load_dword v18, v[62:63], off
	v_lshl_add_u64 v[62:63], v[62:63], 0, s[30:31]
	global_load_dword v19, v[62:63], off
	v_lshl_add_u64 v[62:63], v[62:63], 0, s[30:31]
	global_load_dword v20, v[62:63], off
	v_lshl_add_u64 v[62:63], v[62:63], 0, s[30:31]
	global_load_dword v21, v[62:63], off
	v_lshl_add_u64 v[62:63], v[62:63], 0, s[30:31]
	global_load_dword v22, v[62:63], off
	v_lshl_add_u64 v[62:63], v[62:63], 0, s[30:31]
	global_load_dword v23, v[62:63], off
	v_lshl_add_u64 v[62:63], v[62:63], 0, s[30:31]
	global_load_dword v24, v[62:63], off
	v_lshl_add_u64 v[62:63], v[62:63], 0, s[30:31]
	global_load_dword v25, v[62:63], off
	v_lshl_add_u64 v[62:63], v[62:63], 0, s[30:31]
	global_load_dword v26, v[62:63], off
	v_lshl_add_u64 v[62:63], v[62:63], 0, s[30:31]
	global_load_dword v27, v[62:63], off
	v_lshl_add_u64 v[62:63], v[62:63], 0, s[30:31]
	global_load_dword v28, v[62:63], off
	v_lshl_add_u64 v[62:63], v[62:63], 0, s[30:31]
	global_load_dword v29, v[62:63], off
	v_lshl_add_u64 v[62:63], v[62:63], 0, s[30:31]
	global_load_dword v30, v[62:63], off
	v_lshl_add_u64 v[62:63], v[62:63], 0, s[30:31]
	global_load_dword v31, v[62:63], off
	s_waitcnt vmcnt(16)
	s_barrier
	ds_write_b32 v38, v0 offset:0
	ds_write_b32 v38, v1 offset:1040
	ds_write_b32 v38, v2 offset:2080
	ds_write_b32 v38, v3 offset:3120
	ds_write_b32 v38, v4 offset:4160
	ds_write_b32 v38, v5 offset:5200
	ds_write_b32 v38, v6 offset:6240
	ds_write_b32 v38, v7 offset:7280
	ds_write_b32 v38, v8 offset:8320
	ds_write_b32 v38, v9 offset:9360
	ds_write_b32 v38, v10 offset:10400
	ds_write_b32 v38, v11 offset:11440
	ds_write_b32 v38, v12 offset:12480
	ds_write_b32 v38, v13 offset:13520
	ds_write_b32 v38, v14 offset:14560
	ds_write_b32 v38, v15 offset:15600
	v_lshl_add_u32 v46, v41, s20, v42
	s_waitcnt lgkmcnt(0)
	s_barrier
	ds_read2_b32 v[66:67], v40 offset0:0 offset1:32
	ds_read2_b32 v[68:69], v40 offset0:65 offset1:97
	ds_read2_b32 v[70:71], v40 offset0:130 offset1:162
	ds_read2_b32 v[72:73], v40 offset0:195 offset1:227
	ds_read2_b32 v[74:75], v44 offset0:4 offset1:36
	ds_read2_b32 v[76:77], v44 offset0:69 offset1:101
	ds_read2_b32 v[78:79], v44 offset0:134 offset1:166
	ds_read2_b32 v[80:81], v44 offset0:199 offset1:231
	v_lshl_add_u64 v[48:49], s[16:17], 0, v[46:47]
	v_lshl_add_u64 v[50:51], v[48:49], 0, s[18:19]
	s_waitcnt lgkmcnt(6)
	v_cvt_pk_bf16_f32 v52, v66, v68
	v_cvt_pk_bf16_f32 v56, v67, v69
	s_waitcnt lgkmcnt(4)
	v_cvt_pk_bf16_f32 v53, v70, v72
	v_cvt_pk_bf16_f32 v57, v71, v73
	s_waitcnt lgkmcnt(2)
	v_cvt_pk_bf16_f32 v54, v74, v76
	v_cvt_pk_bf16_f32 v58, v75, v77
	s_waitcnt lgkmcnt(0)
	v_cvt_pk_bf16_f32 v55, v78, v80
	v_cvt_pk_bf16_f32 v59, v79, v81
	global_store_dwordx4 v[48:49], v[52:55], off
	global_store_dwordx4 v[50:51], v[56:59], off
	s_addk_i32 s9, 0x100
	s_cmpk_lt_u32 s9, 0x1740
	s_cbranch_scc0 .Ltrq_last2
	s_cmpk_lt_u32 s9, 0x440
	s_cbranch_scc1 .Ltrq_p5_c0
	s_cmpk_lt_u32 s9, 0xc40
	s_cbranch_scc1 .Ltrq_p5_c1
	s_cmpk_lt_u32 s9, 0x1440
	s_cbranch_scc1 .Ltrq_p5_c2
	s_cmpk_lt_u32 s9, 0x1540
	s_cbranch_scc1 .Ltrq_p5_c3
	s_sub_u32 s7, s9, 0x1540
	s_mov_b64 s[70:71], s[80:81]
	s_mov_b64 s[12:13], s[82:83]
	s_mov_b64 s[16:17], s[86:87]
	s_mov_b32 s8, 10
	s_mov_b32 s22, 10
	s_mov_b32 s21, 1
	s_branch .Ltrq_p5_cm

.Ltrq_l6_x:
	global_load_dword v0, v[60:61], off
	v_lshl_add_u64 v[60:61], v[60:61], 0, s[14:15]
	global_load_dword v1, v[60:61], off
	v_lshl_add_u64 v[60:61], v[60:61], 0, s[14:15]
	global_load_dword v2, v[60:61], off
	v_lshl_add_u64 v[60:61], v[60:61], 0, s[14:15]
	global_load_dword v3, v[60:61], off
	v_lshl_add_u64 v[60:61], v[60:61], 0, s[14:15]
	global_load_dword v4, v[60:61], off
	v_lshl_add_u64 v[60:61], v[60:61], 0, s[14:15]
	global_load_dword v5, v[60:61], off
	v_lshl_add_u64 v[60:61], v[60:61], 0, s[14:15]
	global_load_dword v6, v[60:61], off
	v_lshl_add_u64 v[60:61], v[60:61], 0, s[14:15]
	global_load_dword v7, v[60:61], off
	v_lshl_add_u64 v[60:61], v[60:61], 0, s[14:15]
	global_load_dword v8, v[60:61], off
	v_lshl_add_u64 v[60:61], v[60:61], 0, s[14:15]
	global_load_dword v9, v[60:61], off
	v_lshl_add_u64 v[60:61], v[60:61], 0, s[14:15]
	global_load_dword v10, v[60:61], off
	v_lshl_add_u64 v[60:61], v[60:61], 0, s[14:15]
	global_load_dword v11, v[60:61], off
	v_lshl_add_u64 v[60:61], v[60:61], 0, s[14:15]
	global_load_dword v12, v[60:61], off
	v_lshl_add_u64 v[60:61], v[60:61], 0, s[14:15]
	global_load_dword v13, v[60:61], off
	v_lshl_add_u64 v[60:61], v[60:61], 0, s[14:15]
	global_load_dword v14, v[60:61], off
	v_lshl_add_u64 v[60:61], v[60:61], 0, s[14:15]
	global_load_dword v15, v[60:61], off
	s_waitcnt vmcnt(16)
	s_barrier
	ds_write_b32 v38, v16 offset:0
	ds_write_b32 v38, v17 offset:1040
	ds_write_b32 v38, v18 offset:2080
	ds_write_b32 v38, v19 offset:3120
	ds_write_b32 v38, v20 offset:4160
	ds_write_b32 v38, v21 offset:5200
	ds_write_b32 v38, v22 offset:6240
	ds_write_b32 v38, v23 offset:7280
	ds_write_b32 v38, v24 offset:8320
	ds_write_b32 v38, v25 offset:9360
	ds_write_b32 v38, v26 offset:10400
	ds_write_b32 v38, v27 offset:11440
	ds_write_b32 v38, v28 offset:12480
	ds_write_b32 v38, v29 offset:13520
	ds_write_b32 v38, v30 offset:14560
	ds_write_b32 v38, v31 offset:15600
	v_lshl_add_u32 v46, v41, s90, v42
	s_waitcnt lgkmcnt(0)
	s_barrier
	ds_read2_b32 v[66:67], v40 offset0:0 offset1:32
	ds_read2_b32 v[68:69], v40 offset0:65 offset1:97
	ds_read2_b32 v[70:71], v40 offset0:130 offset1:162
	ds_read2_b32 v[72:73], v40 offset0:195 offset1:227
	ds_read2_b32 v[74:75], v44 offset0:4 offset1:36
	ds_read2_b32 v[76:77], v44 offset0:69 offset1:101
	ds_read2_b32 v[78:79], v44 offset0:134 offset1:166
	ds_read2_b32 v[80:81], v44 offset0:199 offset1:231
	v_lshl_add_u64 v[48:49], s[34:35], 0, v[46:47]
	v_lshl_add_u64 v[50:51], v[48:49], 0, s[88:89]
	s_waitcnt lgkmcnt(6)
	v_cvt_pk_bf16_f32 v52, v66, v68
	v_cvt_pk_bf16_f32 v56, v67, v69
	s_waitcnt lgkmcnt(4)
	v_cvt_pk_bf16_f32 v53, v70, v72
	v_cvt_pk_bf16_f32 v57, v71, v73
	s_waitcnt lgkmcnt(2)
	v_cvt_pk_bf16_f32 v54, v74, v76
	v_cvt_pk_bf16_f32 v58, v75, v77
	s_waitcnt lgkmcnt(0)
	v_cvt_pk_bf16_f32 v55, v78, v80
	v_cvt_pk_bf16_f32 v59, v79, v81
	global_store_dwordx4 v[48:49], v[52:55], off
	global_store_dwordx4 v[50:51], v[56:59], off
	s_branch .Ltrq_loop
.Ltrq_last1:
	s_waitcnt vmcnt(0)
	s_barrier
	ds_write_b32 v38, v0 offset:0
	ds_write_b32 v38, v1 offset:1040
	ds_write_b32 v38, v2 offset:2080
	ds_write_b32 v38, v3 offset:3120
	ds_write_b32 v38, v4 offset:4160
	ds_write_b32 v38, v5 offset:5200
	ds_write_b32 v38, v6 offset:6240
	ds_write_b32 v38, v7 offset:7280
	ds_write_b32 v38, v8 offset:8320
	ds_write_b32 v38, v9 offset:9360
	ds_write_b32 v38, v10 offset:10400
	ds_write_b32 v38, v11 offset:11440
	ds_write_b32 v38, v12 offset:12480
	ds_write_b32 v38, v13 offset:13520
	ds_write_b32 v38, v14 offset:14560
	ds_write_b32 v38, v15 offset:15600
	v_lshl_add_u32 v46, v41, s20, v42
	s_waitcnt lgkmcnt(0)
	s_barrier
	ds_read2_b32 v[66:67], v40 offset0:0 offset1:32
	ds_read2_b32 v[68:69], v40 offset0:65 offset1:97
	ds_read2_b32 v[70:71], v40 offset0:130 offset1:162
	ds_read2_b32 v[72:73], v40 offset0:195 offset1:227
	ds_read2_b32 v[74:75], v44 offset0:4 offset1:36
	ds_read2_b32 v[76:77], v44 offset0:69 offset1:101
	ds_read2_b32 v[78:79], v44 offset0:134 offset1:166
	ds_read2_b32 v[80:81], v44 offset0:199 offset1:231
	v_lshl_add_u64 v[48:49], s[16:17], 0, v[46:47]
	v_lshl_add_u64 v[50:51], v[48:49], 0, s[18:19]
	s_waitcnt lgkmcnt(6)
	v_cvt_pk_bf16_f32 v52, v66, v68
	v_cvt_pk_bf16_f32 v56, v67, v69
	s_waitcnt lgkmcnt(4)
	v_cvt_pk_bf16_f32 v53, v70, v72
	v_cvt_pk_bf16_f32 v57, v71, v73
	s_waitcnt lgkmcnt(2)
	v_cvt_pk_bf16_f32 v54, v74, v76
	v_cvt_pk_bf16_f32 v58, v75, v77
	s_waitcnt lgkmcnt(0)
	v_cvt_pk_bf16_f32 v55, v78, v80
	v_cvt_pk_bf16_f32 v59, v79, v81
	global_store_dwordx4 v[48:49], v[52:55], off
	global_store_dwordx4 v[50:51], v[56:59], off
	s_branch .Ltrq_done
.Ltrq_last2:
	s_waitcnt vmcnt(0)
	s_barrier
	ds_write_b32 v38, v16 offset:0
	ds_write_b32 v38, v17 offset:1040
	ds_write_b32 v38, v18 offset:2080
	ds_write_b32 v38, v19 offset:3120
	ds_write_b32 v38, v20 offset:4160
	ds_write_b32 v38, v21 offset:5200
	ds_write_b32 v38, v22 offset:6240
	ds_write_b32 v38, v23 offset:7280
	ds_write_b32 v38, v24 offset:8320
	ds_write_b32 v38, v25 offset:9360
	ds_write_b32 v38, v26 offset:10400
	ds_write_b32 v38, v27 offset:11440
	ds_write_b32 v38, v28 offset:12480
	ds_write_b32 v38, v29 offset:13520
	ds_write_b32 v38, v30 offset:14560
	ds_write_b32 v38, v31 offset:15600
	v_lshl_add_u32 v46, v41, s90, v42
	s_waitcnt lgkmcnt(0)
	s_barrier
	ds_read2_b32 v[66:67], v40 offset0:0 offset1:32
	ds_read2_b32 v[68:69], v40 offset0:65 offset1:97
	ds_read2_b32 v[70:71], v40 offset0:130 offset1:162
	ds_read2_b32 v[72:73], v40 offset0:195 offset1:227
	ds_read2_b32 v[74:75], v44 offset0:4 offset1:36
	ds_read2_b32 v[76:77], v44 offset0:69 offset1:101
	ds_read2_b32 v[78:79], v44 offset0:134 offset1:166
	ds_read2_b32 v[80:81], v44 offset0:199 offset1:231
	v_lshl_add_u64 v[48:49], s[34:35], 0, v[46:47]
	v_lshl_add_u64 v[50:51], v[48:49], 0, s[88:89]
	s_waitcnt lgkmcnt(6)
	v_cvt_pk_bf16_f32 v52, v66, v68
	v_cvt_pk_bf16_f32 v56, v67, v69
	s_waitcnt lgkmcnt(4)
	v_cvt_pk_bf16_f32 v53, v70, v72
	v_cvt_pk_bf16_f32 v57, v71, v73
	s_waitcnt lgkmcnt(2)
	v_cvt_pk_bf16_f32 v54, v74, v76
	v_cvt_pk_bf16_f32 v58, v75, v77
	s_waitcnt lgkmcnt(0)
	v_cvt_pk_bf16_f32 v55, v78, v80
	v_cvt_pk_bf16_f32 v59, v79, v81
	global_store_dwordx4 v[48:49], v[52:55], off
	global_store_dwordx4 v[50:51], v[56:59], off
